# in-proj rotary epilogue regenerated: per column pair one v_pk_mul (cos via op_sel) + one v_pk_fma (swapped x, -/+ sin via neg_lo) straight from the prefetched rows; 907 -> 306 lines
# speedup vs baseline: 1.0005x; 1.0005x over previous
.LBB0_143:
	s_add_i32 s0, s55, -12
	s_cmp_lt_u32 s0, 6
	v_lshl_add_u32 v170, s56, 8, v166
	v_mov_b32_e32 v160, 1.0
	v_mov_b32_e32 v161, 0
	s_cselect_b64 s[10:11], -1, 0
	s_cmp_gt_u32 s0, 5
	v_mov_b32_e32 v165, 0
	v_mov_b32_e32 v131, 0
	v_mov_b32_e32 v163, 0
	v_mov_b32_e32 v133, 0
	v_mov_b32_e32 v164, 1.0
	v_mov_b32_e32 v130, 1.0
	v_mov_b32_e32 v162, 1.0
	v_mov_b32_e32 v132, 1.0
	s_cbranch_scc1 .Lepi_fast
	v_mov_b32_e32 v245, 0
	v_lshl_or_b32 v158, s55, 8, v168
	v_ashrrev_i32_e32 v159, 31, v158
	v_lshlrev_b32_e32 v244, 8, v170
	v_and_b32_e32 v244, 0x7ff00, v244
	v_lshl_add_u64 v[246:247], v[142:143], 0, v[244:245]
	global_load_dwordx4 v[184:187], v[246:247], off
	v_lshl_add_u64 v[246:247], v[144:145], 0, v[244:245]
	global_load_dwordx4 v[188:191], v[246:247], off
	v_add_u32_e32 v244, 16, v170
	v_lshlrev_b32_e32 v244, 8, v244
	v_and_b32_e32 v244, 0x7ff00, v244
	v_lshl_add_u64 v[246:247], v[142:143], 0, v[244:245]
	global_load_dwordx4 v[192:195], v[246:247], off
	v_lshl_add_u64 v[246:247], v[144:145], 0, v[244:245]
	global_load_dwordx4 v[196:199], v[246:247], off
	v_add_u32_e32 v244, 32, v170
	v_lshlrev_b32_e32 v244, 8, v244
	v_and_b32_e32 v244, 0x7ff00, v244
	v_lshl_add_u64 v[246:247], v[142:143], 0, v[244:245]
	global_load_dwordx4 v[200:203], v[246:247], off
	v_lshl_add_u64 v[246:247], v[144:145], 0, v[244:245]
	global_load_dwordx4 v[216:219], v[246:247], off
	v_add_u32_e32 v244, 48, v170
	v_lshlrev_b32_e32 v244, 8, v244
	v_and_b32_e32 v244, 0x7ff00, v244
	v_lshl_add_u64 v[246:247], v[142:143], 0, v[244:245]
	global_load_dwordx4 v[220:223], v[246:247], off
	v_lshl_add_u64 v[246:247], v[144:145], 0, v[244:245]
	global_load_dwordx4 v[224:227], v[246:247], off
	v_add_u32_e32 v244, 0x80, v170
	v_lshlrev_b32_e32 v244, 8, v244
	v_and_b32_e32 v244, 0x7ff00, v244
	v_lshl_add_u64 v[246:247], v[142:143], 0, v[244:245]
	global_load_dwordx4 v[228:231], v[246:247], off
	v_lshl_add_u64 v[246:247], v[144:145], 0, v[244:245]
	global_load_dwordx4 v[232:235], v[246:247], off
	v_add_u32_e32 v244, 0x90, v170
	v_lshlrev_b32_e32 v244, 8, v244
	v_and_b32_e32 v244, 0x7ff00, v244
	v_lshl_add_u64 v[246:247], v[142:143], 0, v[244:245]
	global_load_dwordx4 v[236:239], v[246:247], off
	v_lshl_add_u64 v[246:247], v[144:145], 0, v[244:245]
	global_load_dwordx4 v[240:243], v[246:247], off
	s_waitcnt vmcnt(10)
	v_mov_b64_e32 v[182:183], s[12:13]
	v_mad_i64_i32 v[182:183], s[0:1], v170, s43, v[182:183]
	v_lshl_add_u64 v[182:183], v[158:159], 1, v[182:183]
	v_pk_mul_f32 v[160:161], v[126:127], v[188:189] op_sel:[0,0] op_sel_hi:[1,0]
	v_pk_fma_f32 v[126:127], v[126:127], v[184:185], v[160:161] op_sel:[1,0,0] op_sel_hi:[0,0,1] neg_lo:[0,1,0]
	v_pk_mul_f32 v[162:163], v[128:129], v[188:189] op_sel:[0,1] op_sel_hi:[1,1]
	v_pk_fma_f32 v[128:129], v[128:129], v[184:185], v[162:163] op_sel:[1,1,0] op_sel_hi:[0,1,1] neg_lo:[0,1,0]
	v_pk_mul_f32 v[164:165], v[122:123], v[190:191] op_sel:[0,0] op_sel_hi:[1,0]
	v_pk_fma_f32 v[122:123], v[122:123], v[186:187], v[164:165] op_sel:[1,0,0] op_sel_hi:[0,0,1] neg_lo:[0,1,0]
	v_pk_mul_f32 v[180:181], v[124:125], v[190:191] op_sel:[0,1] op_sel_hi:[1,1]
	v_pk_fma_f32 v[124:125], v[124:125], v[186:187], v[180:181] op_sel:[1,1,0] op_sel_hi:[0,1,1] neg_lo:[0,1,0]
	v_cvt_pk_bf16_f32 v172, v126, v127
	v_cvt_pk_bf16_f32 v173, v128, v129
	v_cvt_pk_bf16_f32 v174, v122, v123
	v_cvt_pk_bf16_f32 v175, v124, v125
	global_store_dwordx4 v[182:183], v[172:175], off sc1 nt
	v_pk_mul_f32 v[160:161], v[118:119], v[188:189] op_sel:[0,0] op_sel_hi:[1,0]
	v_pk_fma_f32 v[118:119], v[118:119], v[184:185], v[160:161] op_sel:[1,0,0] op_sel_hi:[0,0,1] neg_lo:[0,1,0]
	v_pk_mul_f32 v[162:163], v[120:121], v[188:189] op_sel:[0,1] op_sel_hi:[1,1]
	v_pk_fma_f32 v[120:121], v[120:121], v[184:185], v[162:163] op_sel:[1,1,0] op_sel_hi:[0,1,1] neg_lo:[0,1,0]
	v_pk_mul_f32 v[164:165], v[114:115], v[190:191] op_sel:[0,0] op_sel_hi:[1,0]
	v_pk_fma_f32 v[114:115], v[114:115], v[186:187], v[164:165] op_sel:[1,0,0] op_sel_hi:[0,0,1] neg_lo:[0,1,0]
	v_pk_mul_f32 v[180:181], v[116:117], v[190:191] op_sel:[0,1] op_sel_hi:[1,1]
	v_pk_fma_f32 v[116:117], v[116:117], v[186:187], v[180:181] op_sel:[1,1,0] op_sel_hi:[0,1,1] neg_lo:[0,1,0]
	v_cvt_pk_bf16_f32 v176, v118, v119
	v_cvt_pk_bf16_f32 v177, v120, v121
	v_cvt_pk_bf16_f32 v178, v114, v115
	v_cvt_pk_bf16_f32 v179, v116, v117
	global_store_dwordx4 v[182:183], v[176:179], off offset:256 sc1 nt
	s_waitcnt vmcnt(10)
	v_mov_b64_e32 v[182:183], s[12:13]
	v_add_u32_e32 v181, 16, v170
	v_mad_i64_i32 v[182:183], s[0:1], v181, s43, v[182:183]
	v_lshl_add_u64 v[182:183], v[158:159], 1, v[182:183]
	v_pk_mul_f32 v[160:161], v[110:111], v[196:197] op_sel:[0,0] op_sel_hi:[1,0]
	v_pk_fma_f32 v[110:111], v[110:111], v[192:193], v[160:161] op_sel:[1,0,0] op_sel_hi:[0,0,1] neg_lo:[0,1,0]
	v_pk_mul_f32 v[162:163], v[112:113], v[196:197] op_sel:[0,1] op_sel_hi:[1,1]
	v_pk_fma_f32 v[112:113], v[112:113], v[192:193], v[162:163] op_sel:[1,1,0] op_sel_hi:[0,1,1] neg_lo:[0,1,0]
	v_pk_mul_f32 v[164:165], v[106:107], v[198:199] op_sel:[0,0] op_sel_hi:[1,0]
	v_pk_fma_f32 v[106:107], v[106:107], v[194:195], v[164:165] op_sel:[1,0,0] op_sel_hi:[0,0,1] neg_lo:[0,1,0]
	v_pk_mul_f32 v[180:181], v[108:109], v[198:199] op_sel:[0,1] op_sel_hi:[1,1]
	v_pk_fma_f32 v[108:109], v[108:109], v[194:195], v[180:181] op_sel:[1,1,0] op_sel_hi:[0,1,1] neg_lo:[0,1,0]
	v_cvt_pk_bf16_f32 v172, v110, v111
	v_cvt_pk_bf16_f32 v173, v112, v113
	v_cvt_pk_bf16_f32 v174, v106, v107
	v_cvt_pk_bf16_f32 v175, v108, v109
	global_store_dwordx4 v[182:183], v[172:175], off sc1 nt
	v_pk_mul_f32 v[160:161], v[102:103], v[196:197] op_sel:[0,0] op_sel_hi:[1,0]
	v_pk_fma_f32 v[102:103], v[102:103], v[192:193], v[160:161] op_sel:[1,0,0] op_sel_hi:[0,0,1] neg_lo:[0,1,0]
	v_pk_mul_f32 v[162:163], v[104:105], v[196:197] op_sel:[0,1] op_sel_hi:[1,1]
	v_pk_fma_f32 v[104:105], v[104:105], v[192:193], v[162:163] op_sel:[1,1,0] op_sel_hi:[0,1,1] neg_lo:[0,1,0]
	v_pk_mul_f32 v[164:165], v[98:99], v[198:199] op_sel:[0,0] op_sel_hi:[1,0]
	v_pk_fma_f32 v[98:99], v[98:99], v[194:195], v[164:165] op_sel:[1,0,0] op_sel_hi:[0,0,1] neg_lo:[0,1,0]
	v_pk_mul_f32 v[180:181], v[100:101], v[198:199] op_sel:[0,1] op_sel_hi:[1,1]
	v_pk_fma_f32 v[100:101], v[100:101], v[194:195], v[180:181] op_sel:[1,1,0] op_sel_hi:[0,1,1] neg_lo:[0,1,0]
	v_cvt_pk_bf16_f32 v176, v102, v103
	v_cvt_pk_bf16_f32 v177, v104, v105
	v_cvt_pk_bf16_f32 v178, v98, v99
	v_cvt_pk_bf16_f32 v179, v100, v101
	global_store_dwordx4 v[182:183], v[176:179], off offset:256 sc1 nt
	v_add_u32_e32 v244, 0xa0, v170
	v_lshlrev_b32_e32 v244, 8, v244
	v_and_b32_e32 v244, 0x7ff00, v244
	v_lshl_add_u64 v[246:247], v[142:143], 0, v[244:245]
	global_load_dwordx4 v[184:187], v[246:247], off
	v_lshl_add_u64 v[246:247], v[144:145], 0, v[244:245]
	global_load_dwordx4 v[188:191], v[246:247], off
	v_add_u32_e32 v244, 0xb0, v170
	v_lshlrev_b32_e32 v244, 8, v244
	v_and_b32_e32 v244, 0x7ff00, v244
	v_lshl_add_u64 v[246:247], v[142:143], 0, v[244:245]
	global_load_dwordx4 v[192:195], v[246:247], off
	v_lshl_add_u64 v[246:247], v[144:145], 0, v[244:245]
	global_load_dwordx4 v[196:199], v[246:247], off
	s_waitcnt vmcnt(14)
	v_mov_b64_e32 v[182:183], s[12:13]
	v_add_u32_e32 v181, 32, v170
	v_mad_i64_i32 v[182:183], s[0:1], v181, s43, v[182:183]
	v_lshl_add_u64 v[182:183], v[158:159], 1, v[182:183]
	v_pk_mul_f32 v[160:161], v[94:95], v[216:217] op_sel:[0,0] op_sel_hi:[1,0]
	v_pk_fma_f32 v[94:95], v[94:95], v[200:201], v[160:161] op_sel:[1,0,0] op_sel_hi:[0,0,1] neg_lo:[0,1,0]
	v_pk_mul_f32 v[162:163], v[96:97], v[216:217] op_sel:[0,1] op_sel_hi:[1,1]
	v_pk_fma_f32 v[96:97], v[96:97], v[200:201], v[162:163] op_sel:[1,1,0] op_sel_hi:[0,1,1] neg_lo:[0,1,0]
	v_pk_mul_f32 v[164:165], v[90:91], v[218:219] op_sel:[0,0] op_sel_hi:[1,0]
	v_pk_fma_f32 v[90:91], v[90:91], v[202:203], v[164:165] op_sel:[1,0,0] op_sel_hi:[0,0,1] neg_lo:[0,1,0]
	v_pk_mul_f32 v[180:181], v[92:93], v[218:219] op_sel:[0,1] op_sel_hi:[1,1]
	v_pk_fma_f32 v[92:93], v[92:93], v[202:203], v[180:181] op_sel:[1,1,0] op_sel_hi:[0,1,1] neg_lo:[0,1,0]
	v_cvt_pk_bf16_f32 v172, v94, v95
	v_cvt_pk_bf16_f32 v173, v96, v97
	v_cvt_pk_bf16_f32 v174, v90, v91
	v_cvt_pk_bf16_f32 v175, v92, v93
	global_store_dwordx4 v[182:183], v[172:175], off sc1 nt
	v_pk_mul_f32 v[160:161], v[86:87], v[216:217] op_sel:[0,0] op_sel_hi:[1,0]
	v_pk_fma_f32 v[86:87], v[86:87], v[200:201], v[160:161] op_sel:[1,0,0] op_sel_hi:[0,0,1] neg_lo:[0,1,0]
	v_pk_mul_f32 v[162:163], v[88:89], v[216:217] op_sel:[0,1] op_sel_hi:[1,1]
	v_pk_fma_f32 v[88:89], v[88:89], v[200:201], v[162:163] op_sel:[1,1,0] op_sel_hi:[0,1,1] neg_lo:[0,1,0]
	v_pk_mul_f32 v[164:165], v[82:83], v[218:219] op_sel:[0,0] op_sel_hi:[1,0]
	v_pk_fma_f32 v[82:83], v[82:83], v[202:203], v[164:165] op_sel:[1,0,0] op_sel_hi:[0,0,1] neg_lo:[0,1,0]
	v_pk_mul_f32 v[180:181], v[84:85], v[218:219] op_sel:[0,1] op_sel_hi:[1,1]
	v_pk_fma_f32 v[84:85], v[84:85], v[202:203], v[180:181] op_sel:[1,1,0] op_sel_hi:[0,1,1] neg_lo:[0,1,0]
	v_cvt_pk_bf16_f32 v176, v86, v87
	v_cvt_pk_bf16_f32 v177, v88, v89
	v_cvt_pk_bf16_f32 v178, v82, v83
	v_cvt_pk_bf16_f32 v179, v84, v85
	global_store_dwordx4 v[182:183], v[176:179], off offset:256 sc1 nt
	s_waitcnt vmcnt(14)
	v_mov_b64_e32 v[182:183], s[12:13]
	v_add_u32_e32 v181, 48, v170
	v_mad_i64_i32 v[182:183], s[0:1], v181, s43, v[182:183]
	v_lshl_add_u64 v[182:183], v[158:159], 1, v[182:183]
	v_pk_mul_f32 v[160:161], v[78:79], v[224:225] op_sel:[0,0] op_sel_hi:[1,0]
	v_pk_fma_f32 v[78:79], v[78:79], v[220:221], v[160:161] op_sel:[1,0,0] op_sel_hi:[0,0,1] neg_lo:[0,1,0]
	v_pk_mul_f32 v[162:163], v[80:81], v[224:225] op_sel:[0,1] op_sel_hi:[1,1]
	v_pk_fma_f32 v[80:81], v[80:81], v[220:221], v[162:163] op_sel:[1,1,0] op_sel_hi:[0,1,1] neg_lo:[0,1,0]
	v_pk_mul_f32 v[164:165], v[74:75], v[226:227] op_sel:[0,0] op_sel_hi:[1,0]
	v_pk_fma_f32 v[74:75], v[74:75], v[222:223], v[164:165] op_sel:[1,0,0] op_sel_hi:[0,0,1] neg_lo:[0,1,0]
	v_pk_mul_f32 v[180:181], v[76:77], v[226:227] op_sel:[0,1] op_sel_hi:[1,1]
	v_pk_fma_f32 v[76:77], v[76:77], v[222:223], v[180:181] op_sel:[1,1,0] op_sel_hi:[0,1,1] neg_lo:[0,1,0]
	v_cvt_pk_bf16_f32 v172, v78, v79
	v_cvt_pk_bf16_f32 v173, v80, v81
	v_cvt_pk_bf16_f32 v174, v74, v75
	v_cvt_pk_bf16_f32 v175, v76, v77
	global_store_dwordx4 v[182:183], v[172:175], off sc1 nt
	v_pk_mul_f32 v[160:161], v[70:71], v[224:225] op_sel:[0,0] op_sel_hi:[1,0]
	v_pk_fma_f32 v[70:71], v[70:71], v[220:221], v[160:161] op_sel:[1,0,0] op_sel_hi:[0,0,1] neg_lo:[0,1,0]
	v_pk_mul_f32 v[162:163], v[72:73], v[224:225] op_sel:[0,1] op_sel_hi:[1,1]
	v_pk_fma_f32 v[72:73], v[72:73], v[220:221], v[162:163] op_sel:[1,1,0] op_sel_hi:[0,1,1] neg_lo:[0,1,0]
	v_pk_mul_f32 v[164:165], v[66:67], v[226:227] op_sel:[0,0] op_sel_hi:[1,0]
	v_pk_fma_f32 v[66:67], v[66:67], v[222:223], v[164:165] op_sel:[1,0,0] op_sel_hi:[0,0,1] neg_lo:[0,1,0]
	v_pk_mul_f32 v[180:181], v[68:69], v[226:227] op_sel:[0,1] op_sel_hi:[1,1]
	v_pk_fma_f32 v[68:69], v[68:69], v[222:223], v[180:181] op_sel:[1,1,0] op_sel_hi:[0,1,1] neg_lo:[0,1,0]
	v_cvt_pk_bf16_f32 v176, v70, v71
	v_cvt_pk_bf16_f32 v177, v72, v73
	v_cvt_pk_bf16_f32 v178, v66, v67
	v_cvt_pk_bf16_f32 v179, v68, v69
	global_store_dwordx4 v[182:183], v[176:179], off offset:256 sc1 nt
	s_waitcnt vmcnt(14)
	v_mov_b64_e32 v[182:183], s[12:13]
	v_add_u32_e32 v181, 0x80, v170
	v_mad_i64_i32 v[182:183], s[0:1], v181, s43, v[182:183]
	v_lshl_add_u64 v[182:183], v[158:159], 1, v[182:183]
	v_pk_mul_f32 v[160:161], v[62:63], v[232:233] op_sel:[0,0] op_sel_hi:[1,0]
	v_pk_fma_f32 v[62:63], v[62:63], v[228:229], v[160:161] op_sel:[1,0,0] op_sel_hi:[0,0,1] neg_lo:[0,1,0]
	v_pk_mul_f32 v[162:163], v[64:65], v[232:233] op_sel:[0,1] op_sel_hi:[1,1]
	v_pk_fma_f32 v[64:65], v[64:65], v[228:229], v[162:163] op_sel:[1,1,0] op_sel_hi:[0,1,1] neg_lo:[0,1,0]
	v_pk_mul_f32 v[164:165], v[58:59], v[234:235] op_sel:[0,0] op_sel_hi:[1,0]
	v_pk_fma_f32 v[58:59], v[58:59], v[230:231], v[164:165] op_sel:[1,0,0] op_sel_hi:[0,0,1] neg_lo:[0,1,0]
	v_pk_mul_f32 v[180:181], v[60:61], v[234:235] op_sel:[0,1] op_sel_hi:[1,1]
	v_pk_fma_f32 v[60:61], v[60:61], v[230:231], v[180:181] op_sel:[1,1,0] op_sel_hi:[0,1,1] neg_lo:[0,1,0]
	v_cvt_pk_bf16_f32 v172, v62, v63
	v_cvt_pk_bf16_f32 v173, v64, v65
	v_cvt_pk_bf16_f32 v174, v58, v59
	v_cvt_pk_bf16_f32 v175, v60, v61
	global_store_dwordx4 v[182:183], v[172:175], off sc1 nt
	v_pk_mul_f32 v[160:161], v[54:55], v[232:233] op_sel:[0,0] op_sel_hi:[1,0]
	v_pk_fma_f32 v[54:55], v[54:55], v[228:229], v[160:161] op_sel:[1,0,0] op_sel_hi:[0,0,1] neg_lo:[0,1,0]
	v_pk_mul_f32 v[162:163], v[56:57], v[232:233] op_sel:[0,1] op_sel_hi:[1,1]
	v_pk_fma_f32 v[56:57], v[56:57], v[228:229], v[162:163] op_sel:[1,1,0] op_sel_hi:[0,1,1] neg_lo:[0,1,0]
	v_pk_mul_f32 v[164:165], v[50:51], v[234:235] op_sel:[0,0] op_sel_hi:[1,0]
	v_pk_fma_f32 v[50:51], v[50:51], v[230:231], v[164:165] op_sel:[1,0,0] op_sel_hi:[0,0,1] neg_lo:[0,1,0]
	v_pk_mul_f32 v[180:181], v[52:53], v[234:235] op_sel:[0,1] op_sel_hi:[1,1]
	v_pk_fma_f32 v[52:53], v[52:53], v[230:231], v[180:181] op_sel:[1,1,0] op_sel_hi:[0,1,1] neg_lo:[0,1,0]
	v_cvt_pk_bf16_f32 v176, v54, v55
	v_cvt_pk_bf16_f32 v177, v56, v57
	v_cvt_pk_bf16_f32 v178, v50, v51
	v_cvt_pk_bf16_f32 v179, v52, v53
	global_store_dwordx4 v[182:183], v[176:179], off offset:256 sc1 nt
	s_waitcnt vmcnt(14)
	v_mov_b64_e32 v[182:183], s[12:13]
	v_add_u32_e32 v181, 0x90, v170
	v_mad_i64_i32 v[182:183], s[0:1], v181, s43, v[182:183]
	v_lshl_add_u64 v[182:183], v[158:159], 1, v[182:183]
	v_pk_mul_f32 v[160:161], v[46:47], v[240:241] op_sel:[0,0] op_sel_hi:[1,0]
	v_pk_fma_f32 v[46:47], v[46:47], v[236:237], v[160:161] op_sel:[1,0,0] op_sel_hi:[0,0,1] neg_lo:[0,1,0]
	v_pk_mul_f32 v[162:163], v[48:49], v[240:241] op_sel:[0,1] op_sel_hi:[1,1]
	v_pk_fma_f32 v[48:49], v[48:49], v[236:237], v[162:163] op_sel:[1,1,0] op_sel_hi:[0,1,1] neg_lo:[0,1,0]
	v_pk_mul_f32 v[164:165], v[42:43], v[242:243] op_sel:[0,0] op_sel_hi:[1,0]
	v_pk_fma_f32 v[42:43], v[42:43], v[238:239], v[164:165] op_sel:[1,0,0] op_sel_hi:[0,0,1] neg_lo:[0,1,0]
	v_pk_mul_f32 v[180:181], v[44:45], v[242:243] op_sel:[0,1] op_sel_hi:[1,1]
	v_pk_fma_f32 v[44:45], v[44:45], v[238:239], v[180:181] op_sel:[1,1,0] op_sel_hi:[0,1,1] neg_lo:[0,1,0]
	v_cvt_pk_bf16_f32 v172, v46, v47
	v_cvt_pk_bf16_f32 v173, v48, v49
	v_cvt_pk_bf16_f32 v174, v42, v43
	v_cvt_pk_bf16_f32 v175, v44, v45
	global_store_dwordx4 v[182:183], v[172:175], off sc1 nt
	v_pk_mul_f32 v[160:161], v[38:39], v[240:241] op_sel:[0,0] op_sel_hi:[1,0]
	v_pk_fma_f32 v[38:39], v[38:39], v[236:237], v[160:161] op_sel:[1,0,0] op_sel_hi:[0,0,1] neg_lo:[0,1,0]
	v_pk_mul_f32 v[162:163], v[40:41], v[240:241] op_sel:[0,1] op_sel_hi:[1,1]
	v_pk_fma_f32 v[40:41], v[40:41], v[236:237], v[162:163] op_sel:[1,1,0] op_sel_hi:[0,1,1] neg_lo:[0,1,0]
	v_pk_mul_f32 v[164:165], v[34:35], v[242:243] op_sel:[0,0] op_sel_hi:[1,0]
	v_pk_fma_f32 v[34:35], v[34:35], v[238:239], v[164:165] op_sel:[1,0,0] op_sel_hi:[0,0,1] neg_lo:[0,1,0]
	v_pk_mul_f32 v[180:181], v[36:37], v[242:243] op_sel:[0,1] op_sel_hi:[1,1]
	v_pk_fma_f32 v[36:37], v[36:37], v[238:239], v[180:181] op_sel:[1,1,0] op_sel_hi:[0,1,1] neg_lo:[0,1,0]
	v_cvt_pk_bf16_f32 v176, v38, v39
	v_cvt_pk_bf16_f32 v177, v40, v41
	v_cvt_pk_bf16_f32 v178, v34, v35
	v_cvt_pk_bf16_f32 v179, v36, v37
	global_store_dwordx4 v[182:183], v[176:179], off offset:256 sc1 nt
	s_waitcnt vmcnt(10)
	v_mov_b64_e32 v[182:183], s[12:13]
	v_add_u32_e32 v181, 0xa0, v170
	v_mad_i64_i32 v[182:183], s[0:1], v181, s43, v[182:183]
	v_lshl_add_u64 v[182:183], v[158:159], 1, v[182:183]
	v_pk_mul_f32 v[160:161], v[30:31], v[188:189] op_sel:[0,0] op_sel_hi:[1,0]
	v_pk_fma_f32 v[30:31], v[30:31], v[184:185], v[160:161] op_sel:[1,0,0] op_sel_hi:[0,0,1] neg_lo:[0,1,0]
	v_pk_mul_f32 v[162:163], v[32:33], v[188:189] op_sel:[0,1] op_sel_hi:[1,1]
	v_pk_fma_f32 v[32:33], v[32:33], v[184:185], v[162:163] op_sel:[1,1,0] op_sel_hi:[0,1,1] neg_lo:[0,1,0]
	v_pk_mul_f32 v[164:165], v[26:27], v[190:191] op_sel:[0,0] op_sel_hi:[1,0]
	v_pk_fma_f32 v[26:27], v[26:27], v[186:187], v[164:165] op_sel:[1,0,0] op_sel_hi:[0,0,1] neg_lo:[0,1,0]
	v_pk_mul_f32 v[180:181], v[28:29], v[190:191] op_sel:[0,1] op_sel_hi:[1,1]
	v_pk_fma_f32 v[28:29], v[28:29], v[186:187], v[180:181] op_sel:[1,1,0] op_sel_hi:[0,1,1] neg_lo:[0,1,0]
	v_cvt_pk_bf16_f32 v172, v30, v31
	v_cvt_pk_bf16_f32 v173, v32, v33
	v_cvt_pk_bf16_f32 v174, v26, v27
	v_cvt_pk_bf16_f32 v175, v28, v29
	global_store_dwordx4 v[182:183], v[172:175], off sc1 nt
	v_pk_mul_f32 v[160:161], v[22:23], v[188:189] op_sel:[0,0] op_sel_hi:[1,0]
	v_pk_fma_f32 v[22:23], v[22:23], v[184:185], v[160:161] op_sel:[1,0,0] op_sel_hi:[0,0,1] neg_lo:[0,1,0]
	v_pk_mul_f32 v[162:163], v[24:25], v[188:189] op_sel:[0,1] op_sel_hi:[1,1]
	v_pk_fma_f32 v[24:25], v[24:25], v[184:185], v[162:163] op_sel:[1,1,0] op_sel_hi:[0,1,1] neg_lo:[0,1,0]
	v_pk_mul_f32 v[164:165], v[18:19], v[190:191] op_sel:[0,0] op_sel_hi:[1,0]
	v_pk_fma_f32 v[18:19], v[18:19], v[186:187], v[164:165] op_sel:[1,0,0] op_sel_hi:[0,0,1] neg_lo:[0,1,0]
	v_pk_mul_f32 v[180:181], v[20:21], v[190:191] op_sel:[0,1] op_sel_hi:[1,1]
	v_pk_fma_f32 v[20:21], v[20:21], v[186:187], v[180:181] op_sel:[1,1,0] op_sel_hi:[0,1,1] neg_lo:[0,1,0]
	v_cvt_pk_bf16_f32 v176, v22, v23
	v_cvt_pk_bf16_f32 v177, v24, v25
	v_cvt_pk_bf16_f32 v178, v18, v19
	v_cvt_pk_bf16_f32 v179, v20, v21
	global_store_dwordx4 v[182:183], v[176:179], off offset:256 sc1 nt
	s_waitcnt vmcnt(10)
	v_mov_b64_e32 v[182:183], s[12:13]
	v_add_u32_e32 v181, 0xb0, v170
	v_mad_i64_i32 v[182:183], s[0:1], v181, s43, v[182:183]
	v_lshl_add_u64 v[182:183], v[158:159], 1, v[182:183]
	v_pk_mul_f32 v[160:161], v[14:15], v[196:197] op_sel:[0,0] op_sel_hi:[1,0]
	v_pk_fma_f32 v[14:15], v[14:15], v[192:193], v[160:161] op_sel:[1,0,0] op_sel_hi:[0,0,1] neg_lo:[0,1,0]
	v_pk_mul_f32 v[162:163], v[16:17], v[196:197] op_sel:[0,1] op_sel_hi:[1,1]
	v_pk_fma_f32 v[16:17], v[16:17], v[192:193], v[162:163] op_sel:[1,1,0] op_sel_hi:[0,1,1] neg_lo:[0,1,0]
	v_pk_mul_f32 v[164:165], v[10:11], v[198:199] op_sel:[0,0] op_sel_hi:[1,0]
	v_pk_fma_f32 v[10:11], v[10:11], v[194:195], v[164:165] op_sel:[1,0,0] op_sel_hi:[0,0,1] neg_lo:[0,1,0]
	v_pk_mul_f32 v[180:181], v[12:13], v[198:199] op_sel:[0,1] op_sel_hi:[1,1]
	v_pk_fma_f32 v[12:13], v[12:13], v[194:195], v[180:181] op_sel:[1,1,0] op_sel_hi:[0,1,1] neg_lo:[0,1,0]
	v_cvt_pk_bf16_f32 v172, v14, v15
	v_cvt_pk_bf16_f32 v173, v16, v17
	v_cvt_pk_bf16_f32 v174, v10, v11
	v_cvt_pk_bf16_f32 v175, v12, v13
	global_store_dwordx4 v[182:183], v[172:175], off sc1 nt
	v_pk_mul_f32 v[160:161], v[6:7], v[196:197] op_sel:[0,0] op_sel_hi:[1,0]
	v_pk_fma_f32 v[6:7], v[6:7], v[192:193], v[160:161] op_sel:[1,0,0] op_sel_hi:[0,0,1] neg_lo:[0,1,0]
	v_pk_mul_f32 v[162:163], v[8:9], v[196:197] op_sel:[0,1] op_sel_hi:[1,1]
	v_pk_fma_f32 v[8:9], v[8:9], v[192:193], v[162:163] op_sel:[1,1,0] op_sel_hi:[0,1,1] neg_lo:[0,1,0]
	v_pk_mul_f32 v[164:165], v[2:3], v[198:199] op_sel:[0,0] op_sel_hi:[1,0]
	v_pk_fma_f32 v[2:3], v[2:3], v[194:195], v[164:165] op_sel:[1,0,0] op_sel_hi:[0,0,1] neg_lo:[0,1,0]
	v_pk_mul_f32 v[180:181], v[4:5], v[198:199] op_sel:[0,1] op_sel_hi:[1,1]
	v_pk_fma_f32 v[4:5], v[4:5], v[194:195], v[180:181] op_sel:[1,1,0] op_sel_hi:[0,1,1] neg_lo:[0,1,0]
	v_cvt_pk_bf16_f32 v176, v6, v7
	v_cvt_pk_bf16_f32 v177, v8, v9
	v_cvt_pk_bf16_f32 v178, v2, v3
	v_cvt_pk_bf16_f32 v179, v4, v5
	global_store_dwordx4 v[182:183], v[176:179], off offset:256 sc1 nt
